# all four GEMM phases: first K-tile of every unit peeled, its MFMAs take C=0, the 128 accumulator-clearing v_mov per wave and unit removed
# speedup vs baseline: 1.0114x; 1.0114x over previous
; #define PG8_LAS __attribute__((address_space(3)))
; template <class Epi, class Sched, bool ALIGN_EPI = false, bool SP2 = false, bool F8 = false, bool GATHER = false>
; __device__ __forceinline__ void gemm_phase(PG8_LAS unsigned char* lds, const Gemm g, const Sched& S, const Epi& E, const int tid_in) {
;     ...
;         const bool has_next = S.next(ui + 1, nxt); nxt.par = (ui + 1) & 1;
;         if constexpr (GATHER) { if (has_next && wid == 0)
;             __builtin_amdgcn_global_load_lds((const unsigned*)(g.rowmap + (size_t)nxt.pm * BM + 4 * lane), (PG8_LAS unsigned*)(lds + ROWMAP_LDS_OFF), 16, 0, 0); }
;         const char* nA = (has_next && !GATHER) ? (const char*)g.A + (size_t)nxt.pm * tstep : cA;
;         if constexpr (GATHER) { _Pragma("unroll") for (int _h = 0; _h < 2; ++_h) _Pragma("unroll") for (int _i = 0; _i < 2; ++_i) ga_nxt[_h][_i] = ga_cur[_h][_i]; } const char* nB = has_next ? (const char*)g.Bt + (size_t)nxt.e * g.bstride + (size_t)nxt.pn * tstep : cB;
;     ...
; #pragma unroll
;         for (int a = 0; a < 2; ++a)
; #pragma unroll
;             for (int b = 0; b < 2; ++b)
; #pragma unroll
;                 for (int m = 0; m < 4; ++m)
; #pragma unroll
;                     for (int n = 0; n < 2; ++n) acc[a][b][m][n] = (f32x4){0.f, 0.f, 0.f, 0.f};
.LBB0_155:
	s_ashr_i32 s37, s36, 31
	s_lshl_b64 s[42:43], s[36:37], 19
	v_readlane_b32 s44, v252, 50
	v_readlane_b32 s45, v252, 51
	s_add_u32 s42, s44, s42
	s_addc_u32 s43, s45, s43
	s_and_b64 s[44:45], s[38:39], exec
	s_cselect_b32 s37, s43, s41
	s_cselect_b32 s75, s42, s40
	s_ashr_i32 s23, s22, 31
	s_lshl_b64 s[44:45], s[22:23], 19
	s_add_u32 s44, s4, s44
	s_addc_u32 s45, s21, s45
	s_and_b64 s[50:51], s[38:39], exec
	s_cselect_b32 s23, s45, s49
	s_cselect_b32 s76, s44, s48
	s_cmp_lg_u32 s46, 0
	s_cselect_b64 s[46:47], -1, 0
	s_add_u32 s50, s40, 0x40080
	s_addc_u32 s51, s41, 0
	s_add_u32 s77, s48, 0x100
	v_lshl_add_u64 v[214:215], s[50:51], 0, v[210:211]
	v_lshl_add_u64 v[216:217], s[50:51], 0, v[212:213]
	s_addc_u32 s78, s49, 0
	s_mov_b32 s79, -2
	s_mov_b64 s[48:49], 0
	s_branch .Lpk_inproj_157

; #define PG8_STAGE(bufoff, gbase, voff) do { _Pragma("unroll") for (int _i = 0; _i < 2; ++_i) \
;         __builtin_amdgcn_global_load_lds((const unsigned*)((const char*)(gbase) + (voff)[_i]), (PG8_LAS unsigned*)(lds + (bufoff) + ldsw + _i * 8192), 16, 0, 0); } while (0)
; #define PG8_LDA(dst, b, h) do { _Pragma("unroll") for (int m = 0; m < 4; ++m) _Pragma("unroll") for (int k = 0; k < 2; ++k) dst[m][k] = *(const PG8_LAS bf16x8*)(lds + PG8_SA(b, h) + aoff + m * 2048 + k * 1024); } while (0)
; #define PG8_LDB(dst, b, h) do { _Pragma("unroll") for (int n = 0; n < 2; ++n) _Pragma("unroll") for (int k = 0; k < 2; ++k) dst[n][k] = *(const PG8_LAS bf16x8*)(lds + PG8_SB(b, h) + boff + n * 2048 + k * 1024); } while (0)
; #define PG8_WAIT_VR(relax) do { if (relax) asm volatile("s_waitcnt vmcnt(%0)" :: "n"(8 + Epi::NST) : "memory"); else asm volatile("s_waitcnt vmcnt(8)" ::: "memory"); } while (0)
; #define PG8_WAIT_L(n) asm volatile("s_waitcnt lgkmcnt(" #n ")" ::: "memory")
; #define PG8_BAR __builtin_amdgcn_s_barrier()
; #define PG8_SCHED __builtin_amdgcn_sched_barrier(0)
; template <class Epi, class Sched, bool ALIGN_EPI = false, bool SP2 = false, bool F8 = false, bool GATHER = false>
; __device__ __forceinline__ void gemm_phase(PG8_LAS unsigned char* lds, const Gemm g, const Sched& S, const Epi& E, const int tid_in) {
;     ...
;             const bool relax = SP2 && ALIGN_EPI && t == 0 && ui > 0;
;             if constexpr (SP2) {
;             PG8_LDB(B0, 0, 0); PG8_LDB(B1, 0, 1); PG8_SCHED; PG8_LDA(At, 0, 0); if (!relax) PG8_STAGE(PG8_SA(1, 1), a1 + hstepA, vA1c);
;             PG8_WAIT_VR(relax); PG8_WAIT_L(0); PG8_BAR; PG8_MMA(0, 0, At, B0); PG8_MMA(0, 1, At, B1); PG8_BAR; PG8_SCHED;
.LBB0_167:
	s_andn2_b64 vcc, exec, s[54:55]
	s_cbranch_vccnz .LBB0_156
	s_waitcnt vmcnt(24)
	s_branch .LBB0_156
.Lpk_inproj_157:
	ds_read_b128 v[148:151], v227
	ds_read_b128 v[152:155], v227 offset:1024
	ds_read_b128 v[156:159], v227 offset:2048
	ds_read_b128 v[160:163], v227 offset:3072
	ds_read_b128 v[132:135], v231
	ds_read_b128 v[136:139], v231 offset:1024
	ds_read_b128 v[140:143], v231 offset:2048
	ds_read_b128 v[144:147], v231 offset:3072
	s_cmp_eq_u32 s48, 0
	s_cselect_b64 s[50:51], -1, 0
	ds_read_b128 v[188:191], v232
	ds_read_b128 v[192:195], v232 offset:1024
	ds_read_b128 v[180:183], v232 offset:2048
	ds_read_b128 v[184:187], v232 offset:3072
	ds_read_b128 v[172:175], v232 offset:4096
	ds_read_b128 v[176:179], v232 offset:5120
	ds_read_b128 v[164:167], v232 offset:6144
	ds_read_b128 v[168:171], v232 offset:7168
	s_and_b64 s[50:51], s[46:47], s[50:51]
	s_mov_b64 s[52:53], -1
	s_and_b64 vcc, exec, s[50:51]
	s_cbranch_vccnz .Lpk_inproj_159
	v_lshl_add_u64 v[218:219], v[214:215], 0, s[48:49]
	s_add_i32 m0, s25, 0xc000
	s_mov_b64 s[52:53], 0
	global_load_lds_dwordx4 v[218:219], off
	v_lshl_add_u64 v[218:219], v[216:217], 0, s[48:49]
	s_add_i32 m0, s25, 0xe000
	s_nop 0
	global_load_lds_dwordx4 v[218:219], off
	s_waitcnt vmcnt(8)

; #define PG8_STAGE(bufoff, gbase, voff) do { _Pragma("unroll") for (int _i = 0; _i < 2; ++_i) \
;         __builtin_amdgcn_global_load_lds((const unsigned*)((const char*)(gbase) + (voff)[_i]), (PG8_LAS unsigned*)(lds + (bufoff) + ldsw + _i * 8192), 16, 0, 0); } while (0)
; #define PG8_LDA(dst, b, h) do { _Pragma("unroll") for (int m = 0; m < 4; ++m) _Pragma("unroll") for (int k = 0; k < 2; ++k) dst[m][k] = *(const PG8_LAS bf16x8*)(lds + PG8_SA(b, h) + aoff + m * 2048 + k * 1024); } while (0)
; #define PG8_LDB(dst, b, h) do { _Pragma("unroll") for (int n = 0; n < 2; ++n) _Pragma("unroll") for (int k = 0; k < 2; ++k) dst[n][k] = *(const PG8_LAS bf16x8*)(lds + PG8_SB(b, h) + boff + n * 2048 + k * 1024); } while (0)
; #define PG8_WAIT_VR(relax) do { if (relax) asm volatile("s_waitcnt vmcnt(%0)" :: "n"(8 + Epi::NST) : "memory"); else asm volatile("s_waitcnt vmcnt(8)" ::: "memory"); } while (0)
; #define PG8_WAIT_L(n) asm volatile("s_waitcnt lgkmcnt(" #n ")" ::: "memory")
; #define PG8_BAR __builtin_amdgcn_s_barrier()
; #define PG8_SCHED __builtin_amdgcn_sched_barrier(0)
; template <class Epi, class Sched, bool ALIGN_EPI = false, bool SP2 = false, bool F8 = false, bool GATHER = false>
; __device__ __forceinline__ void gemm_phase(PG8_LAS unsigned char* lds, const Gemm g, const Sched& S, const Epi& E, const int tid_in) {
;     ...
;             const char* a1 = cA + (size_t)(t + 1) * kstep;
;             const char* a2 = last ? nA : cA + (size_t)(t + 2) * kstep; const char* b2 = last ? nB : cB + (size_t)(t + 2) * kstep;
;             const char* a3 = a2 + kstep; const char* b3 = b2 + kstep;
;             if (last && has_next) S.a_ready(nxt);
;             const bool relax = SP2 && ALIGN_EPI && t == 0 && ui > 0;
;             if constexpr (SP2) {
;             PG8_LDB(B0, 0, 0); PG8_LDB(B1, 0, 1); PG8_SCHED; PG8_LDA(At, 0, 0); if (!relax) PG8_STAGE(PG8_SA(1, 1), a1 + hstepA, vA1c);
;             PG8_WAIT_VR(relax); PG8_WAIT_L(0); PG8_BAR; PG8_MMA(0, 0, At, B0); PG8_MMA(0, 1, At, B1); PG8_BAR; PG8_SCHED;
;             PG8_LDA(At, 0, 1); PG8_STAGE(PG8_SB(0, 0), b2, voffB); PG8_STAGE(PG8_SB(0, 1), b2 + hstep, voffB); PG8_STAGE(PG8_SA(0, 0), a2, vA0s);
.Lpk_inproj_161:
	s_xor_b64 s[52:53], s[50:51], -1
	s_add_u32 s50, s40, s48
	s_addc_u32 s51, s41, s49
	s_add_u32 s50, s50, 0x100
	s_addc_u32 s51, s51, 0
	s_add_u32 s56, s77, s48
	s_addc_u32 s57, s78, s49
	s_waitcnt lgkmcnt(0)
	s_cmpk_eq_i32 s48, 0x700
	s_cselect_b32 s55, s37, s51
	s_cselect_b32 s54, s75, s50
	s_cselect_b32 s51, s23, s57
	s_cselect_b32 s50, s76, s56
	s_barrier
	s_setprio 1
	s_waitcnt lgkmcnt(0)
	v_mfma_f32_16x16x32_bf16 v[128:131], v[148:151], v[188:191], 0
	v_mfma_f32_16x16x32_bf16 v[124:127], v[156:159], v[188:191], 0
	v_mfma_f32_16x16x32_bf16 v[120:123], v[148:151], v[180:183], 0
	v_mfma_f32_16x16x32_bf16 v[112:115], v[156:159], v[180:183], 0
	v_mfma_f32_16x16x32_bf16 v[104:107], v[148:151], v[172:175], 0
	v_mfma_f32_16x16x32_bf16 v[96:99], v[156:159], v[172:175], 0
	v_mfma_f32_16x16x32_bf16 v[88:91], v[148:151], v[164:167], 0
	v_mfma_f32_16x16x32_bf16 v[80:83], v[156:159], v[164:167], 0
	v_mfma_f32_16x16x32_bf16 v[128:131], v[152:155], v[192:195], v[128:131]
	v_mfma_f32_16x16x32_bf16 v[124:127], v[160:163], v[192:195], v[124:127]
	v_mfma_f32_16x16x32_bf16 v[120:123], v[152:155], v[184:187], v[120:123]
	v_mfma_f32_16x16x32_bf16 v[112:115], v[160:163], v[184:187], v[112:115]
	v_mfma_f32_16x16x32_bf16 v[104:107], v[152:155], v[176:179], v[104:107]
	v_mfma_f32_16x16x32_bf16 v[96:99], v[160:163], v[176:179], v[96:99]
	v_mfma_f32_16x16x32_bf16 v[88:91], v[152:155], v[168:171], v[88:91]
	v_mfma_f32_16x16x32_bf16 v[80:83], v[160:163], v[168:171], v[80:83]
	s_setprio 0
	s_setprio 1
	v_mfma_f32_16x16x32_bf16 v[116:119], v[132:135], v[188:191], 0
	v_mfma_f32_16x16x32_bf16 v[108:111], v[140:143], v[188:191], 0
	v_mfma_f32_16x16x32_bf16 v[100:103], v[132:135], v[180:183], 0
	v_mfma_f32_16x16x32_bf16 v[92:95], v[140:143], v[180:183], 0
	v_mfma_f32_16x16x32_bf16 v[84:87], v[132:135], v[172:175], 0
	v_mfma_f32_16x16x32_bf16 v[76:79], v[140:143], v[172:175], 0
	v_mfma_f32_16x16x32_bf16 v[72:75], v[132:135], v[164:167], 0
	v_mfma_f32_16x16x32_bf16 v[68:71], v[140:143], v[164:167], 0
	v_mfma_f32_16x16x32_bf16 v[116:119], v[136:139], v[192:195], v[116:119]
	v_mfma_f32_16x16x32_bf16 v[108:111], v[144:147], v[192:195], v[108:111]
	v_mfma_f32_16x16x32_bf16 v[100:103], v[136:139], v[184:187], v[100:103]
	v_mfma_f32_16x16x32_bf16 v[92:95], v[144:147], v[184:187], v[92:95]
	v_mfma_f32_16x16x32_bf16 v[84:87], v[136:139], v[176:179], v[84:87]
	v_mfma_f32_16x16x32_bf16 v[76:79], v[144:147], v[176:179], v[76:79]
	v_mfma_f32_16x16x32_bf16 v[72:75], v[136:139], v[168:171], v[72:75]
	v_mfma_f32_16x16x32_bf16 v[68:71], v[144:147], v[168:171], v[68:71]
	s_setprio 0
	s_barrier
	s_mov_b32 m0, s34
	v_lshl_add_u64 v[218:219], s[50:51], 0, v[206:207]
	s_add_u32 s56, s50, 0x40000
	ds_read_b128 v[188:191], v232 offset:16384
	ds_read_b128 v[192:195], v232 offset:17408
	ds_read_b128 v[180:183], v232 offset:18432
	ds_read_b128 v[184:187], v232 offset:19456
	ds_read_b128 v[172:175], v232 offset:20480
	ds_read_b128 v[176:179], v232 offset:21504
	ds_read_b128 v[164:167], v232 offset:22528
	ds_read_b128 v[168:171], v232 offset:23552
	global_load_lds_dwordx4 v[218:219], off
	v_lshl_add_u64 v[220:221], s[50:51], 0, v[202:203]
	s_mov_b32 m0, s35
	s_addc_u32 s57, s51, 0
	global_load_lds_dwordx4 v[220:221], off
	v_lshl_add_u64 v[222:223], s[56:57], 0, v[206:207]
	s_mov_b32 m0, s58
	v_lshl_add_u64 v[224:225], s[54:55], 0, v[204:205]
	global_load_lds_dwordx4 v[222:223], off
	v_lshl_add_u64 v[222:223], s[56:57], 0, v[202:203]
	s_mov_b32 m0, s59
	s_mov_b64 s[56:57], -1
	global_load_lds_dwordx4 v[222:223], off
	v_lshl_add_u64 v[222:223], s[54:55], 0, v[208:209]
	s_mov_b32 m0, s25
	s_and_b64 vcc, exec, s[52:53]
	global_load_lds_dwordx4 v[222:223], off
	s_mov_b32 m0, s60
	s_nop 0
	global_load_lds_dwordx4 v[224:225], off
	s_cbranch_vccz .Lpk_inproj_163
	s_waitcnt vmcnt(8)
	s_mov_b64 s[56:57], 0

; #define PG8_STAGE(bufoff, gbase, voff) do { _Pragma("unroll") for (int _i = 0; _i < 2; ++_i) \
;         __builtin_amdgcn_global_load_lds((const unsigned*)((const char*)(gbase) + (voff)[_i]), (PG8_LAS unsigned*)(lds + (bufoff) + ldsw + _i * 8192), 16, 0, 0); } while (0)
; #define PG8_LDA(dst, b, h) do { _Pragma("unroll") for (int m = 0; m < 4; ++m) _Pragma("unroll") for (int k = 0; k < 2; ++k) dst[m][k] = *(const PG8_LAS bf16x8*)(lds + PG8_SA(b, h) + aoff + m * 2048 + k * 1024); } while (0)
; #define PG8_LDB(dst, b, h) do { _Pragma("unroll") for (int n = 0; n < 2; ++n) _Pragma("unroll") for (int k = 0; k < 2; ++k) dst[n][k] = *(const PG8_LAS bf16x8*)(lds + PG8_SB(b, h) + boff + n * 2048 + k * 1024); } while (0)
; #define PG8_WAIT_VR(relax) do { if (relax) asm volatile("s_waitcnt vmcnt(%0)" :: "n"(8 + Epi::NST) : "memory"); else asm volatile("s_waitcnt vmcnt(8)" ::: "memory"); } while (0)
; #define PG8_WAIT_L(n) asm volatile("s_waitcnt lgkmcnt(" #n ")" ::: "memory")
; #define PG8_BAR __builtin_amdgcn_s_barrier()
; #define PG8_SCHED __builtin_amdgcn_sched_barrier(0)
; template <class Epi, class Sched, bool ALIGN_EPI = false, bool SP2 = false, bool F8 = false, bool GATHER = false>
; __device__ __forceinline__ void gemm_phase(PG8_LAS unsigned char* lds, const Gemm g, const Sched& S, const Epi& E, const int tid_in) {
;     ...
;             PG8_WAIT_VR(relax); PG8_WAIT_L(0); PG8_BAR; PG8_MMA(1, 0, At, B0); PG8_MMA(1, 1, At, B1); PG8_BAR; PG8_SCHED;
;             PG8_LDB(B0, 1, 0); PG8_LDB(B1, 1, 1); PG8_SCHED; PG8_LDA(At, 1, 0); PG8_STAGE(PG8_SA(0, 1), a2 + hstepA, vA1s);
;             PG8_WAIT_VR(relax); PG8_WAIT_L(0); PG8_BAR; PG8_MMA(0, 0, At, B0); PG8_MMA(0, 1, At, B1); PG8_BAR; PG8_SCHED;
.Lpk_inproj_165:
	s_waitcnt lgkmcnt(0)
	s_barrier
	s_setprio 1
	s_waitcnt lgkmcnt(0)
	v_mfma_f32_16x16x32_bf16 v[46:49], v[148:151], v[188:191], 0
	v_mfma_f32_16x16x32_bf16 v[34:37], v[156:159], v[188:191], 0
	v_mfma_f32_16x16x32_bf16 v[22:25], v[148:151], v[180:183], 0
	v_mfma_f32_16x16x32_bf16 v[18:21], v[156:159], v[180:183], 0
	v_mfma_f32_16x16x32_bf16 v[12:15], v[148:151], v[172:175], 0
	v_mfma_f32_16x16x32_bf16 v[8:11], v[156:159], v[172:175], 0
	v_mfma_f32_16x16x32_bf16 v[4:7], v[148:151], v[164:167], 0
	v_mfma_f32_16x16x32_bf16 v[0:3], v[156:159], v[164:167], 0
	v_mfma_f32_16x16x32_bf16 v[46:49], v[152:155], v[192:195], v[46:49]
	v_mfma_f32_16x16x32_bf16 v[34:37], v[160:163], v[192:195], v[34:37]
	v_mfma_f32_16x16x32_bf16 v[22:25], v[152:155], v[184:187], v[22:25]
	v_mfma_f32_16x16x32_bf16 v[18:21], v[160:163], v[184:187], v[18:21]
	v_mfma_f32_16x16x32_bf16 v[12:15], v[152:155], v[176:179], v[12:15]
	v_mfma_f32_16x16x32_bf16 v[8:11], v[160:163], v[176:179], v[8:11]
	v_mfma_f32_16x16x32_bf16 v[4:7], v[152:155], v[168:171], v[4:7]
	v_mfma_f32_16x16x32_bf16 v[0:3], v[160:163], v[168:171], v[0:3]
	s_setprio 0
	s_setprio 1
	v_mfma_f32_16x16x32_bf16 v[58:61], v[132:135], v[188:191], 0
	v_mfma_f32_16x16x32_bf16 v[62:65], v[140:143], v[188:191], 0
	v_mfma_f32_16x16x32_bf16 v[50:53], v[132:135], v[180:183], 0
	v_mfma_f32_16x16x32_bf16 v[54:57], v[140:143], v[180:183], 0
	v_mfma_f32_16x16x32_bf16 v[38:41], v[132:135], v[172:175], 0
	v_mfma_f32_16x16x32_bf16 v[42:45], v[140:143], v[172:175], 0
	v_mfma_f32_16x16x32_bf16 v[26:29], v[132:135], v[164:167], 0
	v_mfma_f32_16x16x32_bf16 v[30:33], v[140:143], v[164:167], 0
	v_mfma_f32_16x16x32_bf16 v[58:61], v[136:139], v[192:195], v[58:61]
	v_mfma_f32_16x16x32_bf16 v[62:65], v[144:147], v[192:195], v[62:65]
	v_mfma_f32_16x16x32_bf16 v[50:53], v[136:139], v[184:187], v[50:53]
	v_mfma_f32_16x16x32_bf16 v[54:57], v[144:147], v[184:187], v[54:57]
	v_mfma_f32_16x16x32_bf16 v[38:41], v[136:139], v[176:179], v[38:41]
	v_mfma_f32_16x16x32_bf16 v[42:45], v[144:147], v[176:179], v[42:45]
	v_mfma_f32_16x16x32_bf16 v[26:29], v[136:139], v[168:171], v[26:29]
	v_mfma_f32_16x16x32_bf16 v[30:33], v[144:147], v[168:171], v[30:33]
	s_setprio 0
	s_barrier
	v_add_u32_e32 v132, 0x18000, v226
	v_add_u32_e32 v144, 0x1c000, v226
	ds_read_b128 v[148:151], v132
	ds_read_b128 v[152:155], v132 offset:1024
	ds_read_b128 v[156:159], v132 offset:2048
	ds_read_b128 v[160:163], v132 offset:3072
	ds_read_b128 v[132:135], v144
	ds_read_b128 v[136:139], v144 offset:1024
	ds_read_b128 v[140:143], v144 offset:2048
	ds_read_b128 v[144:147], v144 offset:3072
	s_add_u32 s54, s54, 0x40000
	s_addc_u32 s55, s55, 0
	s_mov_b32 m0, s61
	v_lshl_add_u64 v[242:243], s[54:55], 0, v[208:209]
	ds_read_b128 v[188:191], v232 offset:32768
	ds_read_b128 v[192:195], v232 offset:33792
	ds_read_b128 v[180:183], v232 offset:34816
	ds_read_b128 v[184:187], v232 offset:35840
	ds_read_b128 v[172:175], v232 offset:36864
	ds_read_b128 v[176:179], v232 offset:37888
	ds_read_b128 v[164:167], v232 offset:38912
	ds_read_b128 v[168:171], v232 offset:39936
	global_load_lds_dwordx4 v[242:243], off
	v_lshl_add_u64 v[242:243], s[54:55], 0, v[204:205]
	s_mov_b32 m0, s62
	s_mov_b64 s[54:55], -1
	global_load_lds_dwordx4 v[242:243], off
	s_and_b64 vcc, exec, s[52:53]
	s_cbranch_vccz .Lpk_inproj_167
	s_waitcnt vmcnt(8)
	s_mov_b64 s[54:55], 0

; #define PG8_STAGE(bufoff, gbase, voff) do { _Pragma("unroll") for (int _i = 0; _i < 2; ++_i) \
;         __builtin_amdgcn_global_load_lds((const unsigned*)((const char*)(gbase) + (voff)[_i]), (PG8_LAS unsigned*)(lds + (bufoff) + ldsw + _i * 8192), 16, 0, 0); } while (0)
; #define PG8_LDA(dst, b, h) do { _Pragma("unroll") for (int m = 0; m < 4; ++m) _Pragma("unroll") for (int k = 0; k < 2; ++k) dst[m][k] = *(const PG8_LAS bf16x8*)(lds + PG8_SA(b, h) + aoff + m * 2048 + k * 1024); } while (0)
; #define PG8_LDB(dst, b, h) do { _Pragma("unroll") for (int n = 0; n < 2; ++n) _Pragma("unroll") for (int k = 0; k < 2; ++k) dst[n][k] = *(const PG8_LAS bf16x8*)(lds + PG8_SB(b, h) + boff + n * 2048 + k * 1024); } while (0)
; #define PG8_WAIT_VR(relax) do { if (relax) asm volatile("s_waitcnt vmcnt(%0)" :: "n"(8 + Epi::NST) : "memory"); else asm volatile("s_waitcnt vmcnt(8)" ::: "memory"); } while (0)
; #define PG8_WAIT_L(n) asm volatile("s_waitcnt lgkmcnt(" #n ")" ::: "memory")
; #define PG8_BAR __builtin_amdgcn_s_barrier()
; #define PG8_SCHED __builtin_amdgcn_sched_barrier(0)
; template <class Epi, class Sched, bool ALIGN_EPI = false, bool SP2 = false, bool F8 = false, bool GATHER = false>
; __device__ __forceinline__ void gemm_phase(PG8_LAS unsigned char* lds, const Gemm g, const Sched& S, const Epi& E, const int tid_in) {
;     ...
;             PG8_LDB(B0, 0, 0); PG8_LDB(B1, 0, 1); PG8_SCHED; PG8_LDA(At, 0, 0); if (!relax) PG8_STAGE(PG8_SA(1, 1), a1 + hstepA, vA1c);
;             PG8_WAIT_VR(relax); PG8_WAIT_L(0); PG8_BAR; PG8_MMA(0, 0, At, B0); PG8_MMA(0, 1, At, B1); PG8_BAR; PG8_SCHED;
.LBB0_731:
	s_andn2_b64 vcc, exec, s[54:55]
	s_cbranch_vccnz .LBB0_720
	s_waitcnt vmcnt(24)
	s_branch .LBB0_720
.Lpk_outproj_721:
	v_add_u32_e32 v132, 0x10000, v226
	v_add_u32_e32 v144, 0x14000, v226
	ds_read_b128 v[148:151], v132
	ds_read_b128 v[152:155], v132 offset:1024
	ds_read_b128 v[156:159], v132 offset:2048
	ds_read_b128 v[160:163], v132 offset:3072
	ds_read_b128 v[132:135], v144
	ds_read_b128 v[136:139], v144 offset:1024
	ds_read_b128 v[140:143], v144 offset:2048
	ds_read_b128 v[144:147], v144 offset:3072
	s_cmp_eq_u32 s48, 0
	s_cselect_b64 s[50:51], -1, 0
	ds_read_b128 v[188:191], v227
	ds_read_b128 v[192:195], v227 offset:1024
	ds_read_b128 v[180:183], v227 offset:2048
	ds_read_b128 v[184:187], v227 offset:3072
	ds_read_b128 v[172:175], v227 offset:4096
	ds_read_b128 v[176:179], v227 offset:5120
	ds_read_b128 v[164:167], v227 offset:6144
	ds_read_b128 v[168:171], v227 offset:7168
	s_and_b64 s[50:51], s[46:47], s[50:51]
	s_mov_b64 s[52:53], -1
	s_and_b64 vcc, exec, s[50:51]
	s_cbranch_vccnz .Lpk_outproj_723
	v_lshl_add_u64 v[218:219], v[214:215], 0, s[48:49]
	s_add_i32 m0, s25, 0xc000
	s_mov_b64 s[52:53], 0
	global_load_lds_dwordx4 v[218:219], off
	v_lshl_add_u64 v[218:219], v[216:217], 0, s[48:49]
	s_add_i32 m0, s25, 0xe000
	s_nop 0
	global_load_lds_dwordx4 v[218:219], off
	s_waitcnt vmcnt(8)

; #define PG8_STAGE(bufoff, gbase, voff) do { _Pragma("unroll") for (int _i = 0; _i < 2; ++_i) \
;         __builtin_amdgcn_global_load_lds((const unsigned*)((const char*)(gbase) + (voff)[_i]), (PG8_LAS unsigned*)(lds + (bufoff) + ldsw + _i * 8192), 16, 0, 0); } while (0)
; #define PG8_LDA(dst, b, h) do { _Pragma("unroll") for (int m = 0; m < 4; ++m) _Pragma("unroll") for (int k = 0; k < 2; ++k) dst[m][k] = *(const PG8_LAS bf16x8*)(lds + PG8_SA(b, h) + aoff + m * 2048 + k * 1024); } while (0)
; #define PG8_LDB(dst, b, h) do { _Pragma("unroll") for (int n = 0; n < 2; ++n) _Pragma("unroll") for (int k = 0; k < 2; ++k) dst[n][k] = *(const PG8_LAS bf16x8*)(lds + PG8_SB(b, h) + boff + n * 2048 + k * 1024); } while (0)
; #define PG8_WAIT_VR(relax) do { if (relax) asm volatile("s_waitcnt vmcnt(%0)" :: "n"(8 + Epi::NST) : "memory"); else asm volatile("s_waitcnt vmcnt(8)" ::: "memory"); } while (0)
; #define PG8_WAIT_L(n) asm volatile("s_waitcnt lgkmcnt(" #n ")" ::: "memory")
; #define PG8_BAR __builtin_amdgcn_s_barrier()
; #define PG8_SCHED __builtin_amdgcn_sched_barrier(0)
; template <class Epi, class Sched, bool ALIGN_EPI = false, bool SP2 = false, bool F8 = false, bool GATHER = false>
; __device__ __forceinline__ void gemm_phase(PG8_LAS unsigned char* lds, const Gemm g, const Sched& S, const Epi& E, const int tid_in) {
;     ...
;             const char* a2 = last ? nA : cA + (size_t)(t + 2) * kstep; const char* b2 = last ? nB : cB + (size_t)(t + 2) * kstep;
;             const char* a3 = a2 + kstep; const char* b3 = b2 + kstep;
;             if (last && has_next) S.a_ready(nxt);
;             const bool relax = SP2 && ALIGN_EPI && t == 0 && ui > 0;
;             if constexpr (SP2) {
;             PG8_LDB(B0, 0, 0); PG8_LDB(B1, 0, 1); PG8_SCHED; PG8_LDA(At, 0, 0); if (!relax) PG8_STAGE(PG8_SA(1, 1), a1 + hstepA, vA1c);
;             PG8_WAIT_VR(relax); PG8_WAIT_L(0); PG8_BAR; PG8_MMA(0, 0, At, B0); PG8_MMA(0, 1, At, B1); PG8_BAR; PG8_SCHED;
;             PG8_LDA(At, 0, 1); PG8_STAGE(PG8_SB(0, 0), b2, voffB); PG8_STAGE(PG8_SB(0, 1), b2 + hstep, voffB); PG8_STAGE(PG8_SA(0, 0), a2, vA0s);
.Lpk_outproj_725:
	s_xor_b64 s[52:53], s[50:51], -1
	s_add_u32 s50, s40, s48
	s_addc_u32 s51, s41, s49
	s_add_u32 s50, s50, 0x100
	s_addc_u32 s51, s51, 0
	s_add_u32 s56, s77, s48
	s_addc_u32 s57, s78, s49
	s_waitcnt lgkmcnt(0)
	s_cmpk_eq_i32 s48, 0x700
	s_cselect_b32 s55, s37, s51
	s_cselect_b32 s54, s75, s50
	s_cselect_b32 s51, s23, s57
	s_cselect_b32 s50, s76, s56
	s_barrier
	s_setprio 1
	s_waitcnt lgkmcnt(0)
	v_mfma_f32_16x16x32_bf16 v[128:131], v[148:151], v[188:191], 0
	v_mfma_f32_16x16x32_bf16 v[124:127], v[156:159], v[188:191], 0
	v_mfma_f32_16x16x32_bf16 v[120:123], v[148:151], v[180:183], 0
	v_mfma_f32_16x16x32_bf16 v[112:115], v[156:159], v[180:183], 0
	v_mfma_f32_16x16x32_bf16 v[104:107], v[148:151], v[172:175], 0
	v_mfma_f32_16x16x32_bf16 v[96:99], v[156:159], v[172:175], 0
	v_mfma_f32_16x16x32_bf16 v[88:91], v[148:151], v[164:167], 0
	v_mfma_f32_16x16x32_bf16 v[80:83], v[156:159], v[164:167], 0
	v_mfma_f32_16x16x32_bf16 v[128:131], v[152:155], v[192:195], v[128:131]
	v_mfma_f32_16x16x32_bf16 v[124:127], v[160:163], v[192:195], v[124:127]
	v_mfma_f32_16x16x32_bf16 v[120:123], v[152:155], v[184:187], v[120:123]
	v_mfma_f32_16x16x32_bf16 v[112:115], v[160:163], v[184:187], v[112:115]
	v_mfma_f32_16x16x32_bf16 v[104:107], v[152:155], v[176:179], v[104:107]
	v_mfma_f32_16x16x32_bf16 v[96:99], v[160:163], v[176:179], v[96:99]
	v_mfma_f32_16x16x32_bf16 v[88:91], v[152:155], v[168:171], v[88:91]
	v_mfma_f32_16x16x32_bf16 v[80:83], v[160:163], v[168:171], v[80:83]
	s_setprio 0
	s_setprio 1
	v_mfma_f32_16x16x32_bf16 v[116:119], v[132:135], v[188:191], 0
	v_mfma_f32_16x16x32_bf16 v[108:111], v[140:143], v[188:191], 0
	v_mfma_f32_16x16x32_bf16 v[100:103], v[132:135], v[180:183], 0
	v_mfma_f32_16x16x32_bf16 v[92:95], v[140:143], v[180:183], 0
	v_mfma_f32_16x16x32_bf16 v[84:87], v[132:135], v[172:175], 0
	v_mfma_f32_16x16x32_bf16 v[76:79], v[140:143], v[172:175], 0
	v_mfma_f32_16x16x32_bf16 v[72:75], v[132:135], v[164:167], 0
	v_mfma_f32_16x16x32_bf16 v[68:71], v[140:143], v[164:167], 0
	v_mfma_f32_16x16x32_bf16 v[116:119], v[136:139], v[192:195], v[116:119]
	v_mfma_f32_16x16x32_bf16 v[108:111], v[144:147], v[192:195], v[108:111]
	v_mfma_f32_16x16x32_bf16 v[100:103], v[136:139], v[184:187], v[100:103]
	v_mfma_f32_16x16x32_bf16 v[92:95], v[144:147], v[184:187], v[92:95]
	v_mfma_f32_16x16x32_bf16 v[84:87], v[136:139], v[176:179], v[84:87]
	v_mfma_f32_16x16x32_bf16 v[76:79], v[144:147], v[176:179], v[76:79]
	v_mfma_f32_16x16x32_bf16 v[72:75], v[136:139], v[168:171], v[72:75]
	v_mfma_f32_16x16x32_bf16 v[68:71], v[144:147], v[168:171], v[68:71]
	s_setprio 0
	s_barrier
	s_mov_b32 m0, s34
	v_lshl_add_u64 v[218:219], s[50:51], 0, v[206:207]
	s_add_u32 s56, s50, 0x40000
	ds_read_b128 v[188:191], v227 offset:16384
	ds_read_b128 v[192:195], v227 offset:17408
	ds_read_b128 v[180:183], v227 offset:18432
	ds_read_b128 v[184:187], v227 offset:19456
	ds_read_b128 v[172:175], v227 offset:20480
	ds_read_b128 v[176:179], v227 offset:21504
	ds_read_b128 v[164:167], v227 offset:22528
	ds_read_b128 v[168:171], v227 offset:23552
	global_load_lds_dwordx4 v[218:219], off
	v_lshl_add_u64 v[220:221], s[50:51], 0, v[202:203]
	s_mov_b32 m0, s35
	s_addc_u32 s57, s51, 0
	global_load_lds_dwordx4 v[220:221], off
	v_lshl_add_u64 v[222:223], s[56:57], 0, v[206:207]
	s_mov_b32 m0, s58
	v_lshl_add_u64 v[224:225], s[54:55], 0, v[204:205]
	global_load_lds_dwordx4 v[222:223], off
	v_lshl_add_u64 v[222:223], s[56:57], 0, v[202:203]
	s_mov_b32 m0, s59
	s_mov_b64 s[56:57], -1
	global_load_lds_dwordx4 v[222:223], off
	v_lshl_add_u64 v[222:223], s[54:55], 0, v[208:209]
	s_mov_b32 m0, s25
	s_and_b64 vcc, exec, s[52:53]
	global_load_lds_dwordx4 v[222:223], off
	s_mov_b32 m0, s60
	s_nop 0
	global_load_lds_dwordx4 v[224:225], off
	s_cbranch_vccz .Lpk_outproj_727
	s_waitcnt vmcnt(8)
	s_mov_b64 s[56:57], 0

; #define PG8_STAGE(bufoff, gbase, voff) do { _Pragma("unroll") for (int _i = 0; _i < 2; ++_i) \
;         __builtin_amdgcn_global_load_lds((const unsigned*)((const char*)(gbase) + (voff)[_i]), (PG8_LAS unsigned*)(lds + (bufoff) + ldsw + _i * 8192), 16, 0, 0); } while (0)
; #define PG8_LDA(dst, b, h) do { _Pragma("unroll") for (int m = 0; m < 4; ++m) _Pragma("unroll") for (int k = 0; k < 2; ++k) dst[m][k] = *(const PG8_LAS bf16x8*)(lds + PG8_SA(b, h) + aoff + m * 2048 + k * 1024); } while (0)
; #define PG8_LDB(dst, b, h) do { _Pragma("unroll") for (int n = 0; n < 2; ++n) _Pragma("unroll") for (int k = 0; k < 2; ++k) dst[n][k] = *(const PG8_LAS bf16x8*)(lds + PG8_SB(b, h) + boff + n * 2048 + k * 1024); } while (0)
; #define PG8_WAIT_VR(relax) do { if (relax) asm volatile("s_waitcnt vmcnt(%0)" :: "n"(8 + Epi::NST) : "memory"); else asm volatile("s_waitcnt vmcnt(8)" ::: "memory"); } while (0)
; #define PG8_WAIT_L(n) asm volatile("s_waitcnt lgkmcnt(" #n ")" ::: "memory")
; #define PG8_BAR __builtin_amdgcn_s_barrier()
; #define PG8_SCHED __builtin_amdgcn_sched_barrier(0)
; template <class Epi, class Sched, bool ALIGN_EPI = false, bool SP2 = false, bool F8 = false, bool GATHER = false>
; __device__ __forceinline__ void gemm_phase(PG8_LAS unsigned char* lds, const Gemm g, const Sched& S, const Epi& E, const int tid_in) {
;     ...
;             PG8_WAIT_VR(relax); PG8_WAIT_L(0); PG8_BAR; PG8_MMA(1, 0, At, B0); PG8_MMA(1, 1, At, B1); PG8_BAR; PG8_SCHED;
;             PG8_LDB(B0, 1, 0); PG8_LDB(B1, 1, 1); PG8_SCHED; PG8_LDA(At, 1, 0); PG8_STAGE(PG8_SA(0, 1), a2 + hstepA, vA1s);
;             PG8_WAIT_VR(relax); PG8_WAIT_L(0); PG8_BAR; PG8_MMA(0, 0, At, B0); PG8_MMA(0, 1, At, B1); PG8_BAR; PG8_SCHED;
.Lpk_outproj_729:
	s_waitcnt lgkmcnt(0)
	s_barrier
	s_setprio 1
	s_waitcnt lgkmcnt(0)
	v_mfma_f32_16x16x32_bf16 v[46:49], v[148:151], v[188:191], 0
	v_mfma_f32_16x16x32_bf16 v[42:45], v[156:159], v[188:191], 0
	v_mfma_f32_16x16x32_bf16 v[30:33], v[148:151], v[180:183], 0
	v_mfma_f32_16x16x32_bf16 v[18:21], v[156:159], v[180:183], 0
	v_mfma_f32_16x16x32_bf16 v[12:15], v[148:151], v[172:175], 0
	v_mfma_f32_16x16x32_bf16 v[8:11], v[156:159], v[172:175], 0
	v_mfma_f32_16x16x32_bf16 v[4:7], v[148:151], v[164:167], 0
	v_mfma_f32_16x16x32_bf16 v[0:3], v[156:159], v[164:167], 0
	v_mfma_f32_16x16x32_bf16 v[46:49], v[152:155], v[192:195], v[46:49]
	v_mfma_f32_16x16x32_bf16 v[42:45], v[160:163], v[192:195], v[42:45]
	v_mfma_f32_16x16x32_bf16 v[30:33], v[152:155], v[184:187], v[30:33]
	v_mfma_f32_16x16x32_bf16 v[18:21], v[160:163], v[184:187], v[18:21]
	v_mfma_f32_16x16x32_bf16 v[12:15], v[152:155], v[176:179], v[12:15]
	v_mfma_f32_16x16x32_bf16 v[8:11], v[160:163], v[176:179], v[8:11]
	v_mfma_f32_16x16x32_bf16 v[4:7], v[152:155], v[168:171], v[4:7]
	v_mfma_f32_16x16x32_bf16 v[0:3], v[160:163], v[168:171], v[0:3]
	s_setprio 0
	s_setprio 1
	v_mfma_f32_16x16x32_bf16 v[58:61], v[132:135], v[188:191], 0
	v_mfma_f32_16x16x32_bf16 v[62:65], v[140:143], v[188:191], 0
	v_mfma_f32_16x16x32_bf16 v[50:53], v[132:135], v[180:183], 0
	v_mfma_f32_16x16x32_bf16 v[54:57], v[140:143], v[180:183], 0
	v_mfma_f32_16x16x32_bf16 v[34:37], v[132:135], v[172:175], 0
	v_mfma_f32_16x16x32_bf16 v[38:41], v[140:143], v[172:175], 0
	v_mfma_f32_16x16x32_bf16 v[22:25], v[132:135], v[164:167], 0
	v_mfma_f32_16x16x32_bf16 v[26:29], v[140:143], v[164:167], 0
	v_mfma_f32_16x16x32_bf16 v[58:61], v[136:139], v[192:195], v[58:61]
	v_mfma_f32_16x16x32_bf16 v[62:65], v[144:147], v[192:195], v[62:65]
	v_mfma_f32_16x16x32_bf16 v[50:53], v[136:139], v[184:187], v[50:53]
	v_mfma_f32_16x16x32_bf16 v[54:57], v[144:147], v[184:187], v[54:57]
	v_mfma_f32_16x16x32_bf16 v[34:37], v[136:139], v[176:179], v[34:37]
	v_mfma_f32_16x16x32_bf16 v[38:41], v[144:147], v[176:179], v[38:41]
	v_mfma_f32_16x16x32_bf16 v[22:25], v[136:139], v[168:171], v[22:25]
	v_mfma_f32_16x16x32_bf16 v[26:29], v[144:147], v[168:171], v[26:29]
	s_setprio 0
	s_barrier
	v_add_u32_e32 v132, 0x18000, v226
	v_add_u32_e32 v144, 0x1c000, v226
	ds_read_b128 v[148:151], v132
	ds_read_b128 v[152:155], v132 offset:1024
	ds_read_b128 v[156:159], v132 offset:2048
	ds_read_b128 v[160:163], v132 offset:3072
	ds_read_b128 v[132:135], v144
	ds_read_b128 v[136:139], v144 offset:1024
	ds_read_b128 v[140:143], v144 offset:2048
	ds_read_b128 v[144:147], v144 offset:3072
	s_add_u32 s54, s54, 0x40000
	s_addc_u32 s55, s55, 0
	s_mov_b32 m0, s61
	v_lshl_add_u64 v[242:243], s[54:55], 0, v[208:209]
	ds_read_b128 v[188:191], v227 offset:32768
	ds_read_b128 v[192:195], v227 offset:33792
	ds_read_b128 v[180:183], v227 offset:34816
	ds_read_b128 v[184:187], v227 offset:35840
	ds_read_b128 v[172:175], v227 offset:36864
	ds_read_b128 v[176:179], v227 offset:37888
	ds_read_b128 v[164:167], v227 offset:38912
	ds_read_b128 v[168:171], v227 offset:39936
	global_load_lds_dwordx4 v[242:243], off
	v_lshl_add_u64 v[242:243], s[54:55], 0, v[204:205]
	s_mov_b32 m0, s62
	s_mov_b64 s[54:55], -1
	global_load_lds_dwordx4 v[242:243], off
	s_and_b64 vcc, exec, s[52:53]
	s_cbranch_vccz .Lpk_outproj_731
	s_waitcnt vmcnt(8)
	s_mov_b64 s[54:55], 0

; #define PG8_LAS __attribute__((address_space(3)))
; template <class Epi, class Sched, bool ALIGN_EPI = false, bool SP2 = false, bool F8 = false, bool GATHER = false>
; __device__ __forceinline__ void gemm_phase(PG8_LAS unsigned char* lds, const Gemm g, const Sched& S, const Epi& E, const int tid_in) {
;     ...
;         const bool has_next = S.next(ui + 1, nxt); nxt.par = (ui + 1) & 1;
;         if constexpr (GATHER) { if (has_next && wid == 0)
;             __builtin_amdgcn_global_load_lds((const unsigned*)(g.rowmap + (size_t)nxt.pm * BM + 4 * lane), (PG8_LAS unsigned*)(lds + ROWMAP_LDS_OFF), 16, 0, 0); }
;         const char* nA = (has_next && !GATHER) ? (const char*)g.A + (size_t)nxt.pm * tstep : cA;
;         if constexpr (GATHER) { _Pragma("unroll") for (int _h = 0; _h < 2; ++_h) _Pragma("unroll") for (int _i = 0; _i < 2; ++_i) ga_nxt[_h][_i] = ga_cur[_h][_i]; } const char* nB = has_next ? (const char*)g.Bt + (size_t)nxt.e * g.bstride + (size_t)nxt.pn * tstep : cB;
;     ...
;         for (int a = 0; a < 2; ++a)
; #pragma unroll
;             for (int b = 0; b < 2; ++b)
; #pragma unroll
;                 for (int m = 0; m < 4; ++m)
; #pragma unroll
;                     for (int n = 0; n < 2; ++n) acc[a][b][m][n] = (f32x4){0.f, 0.f, 0.f, 0.f};
;         cur = nxt; cA = nA; cB = nB; ++ui; E.prefetch(cur, wid, lane, lds);
;         if constexpr (GATHER) { _Pragma("unroll") for (int _h = 0; _h < 2; ++_h) _Pragma("unroll") for (int _i = 0; _i < 2; ++_i) ga_cur[_h][_i] = ga_nxt[_h][_i]; vA0c[0] = ga_cur[0][0]; vA0c[1] = ga_cur[0][1]; }
.LBB0_1000:
	s_ashr_i32 s57, s56, 31
	s_lshl_b64 s[8:9], s[56:57], 21
	s_add_u32 s3, s74, s8
	s_addc_u32 s34, s75, s9
	s_ashr_i32 s53, s52, 31
	s_lshl_b64 s[8:9], s[52:53], 18
	s_add_u32 s58, s3, s8
	s_addc_u32 s59, s34, s9
	s_and_b64 s[8:9], s[44:45], exec
	s_cselect_b32 s3, s59, s37
	s_cselect_b32 s34, s58, s36
	s_cmp_lg_u32 s35, 0
	v_readlane_b32 s42, v252, 31
	s_cselect_b64 s[8:9], -1, 0
	v_mov_b32_e32 v213, v16
	v_mov_b32_e32 v215, v16
	v_readlane_b32 s43, v252, 32
	s_add_u32 s35, s36, 0x100
	v_lshl_add_u64 v[216:217], s[42:43], 0, v[214:215]
	v_lshl_add_u64 v[218:219], s[42:43], 0, v[212:213]
	s_addc_u32 s53, s37, 0
	s_mov_b32 s55, -2
	s_mov_b64 s[36:37], 0
	v_mov_b32_e32 v232, v214
	v_mov_b32_e32 v213, v212
	v_mov_b32_e32 v234, v210
	v_mov_b32_e32 v215, v208
	s_branch .Lpk_g1_1002

; #define PG8_LOADGA_LDS(dst) do { _Pragma("unroll") for (int _i = 0; _i < 2; ++_i) { int _R, _C; stage_rc(tid * 16 + _i * 8192, _R, _C); _Pragma("unroll") for (int _h = 0; _h < 2; ++_h) \
;         dst[_h][_i] = (unsigned)((const PG8_LAS int*)(lds + ROWMAP_LDS_OFF))[_R + HALF * _h] * (unsigned)(K * 2) + (unsigned)_C * 2u; } } while (0)
; template <class Epi, class Sched, bool ALIGN_EPI = false, bool SP2 = false, bool F8 = false, bool GATHER = false>
; __device__ __forceinline__ void gemm_phase(PG8_LAS unsigned char* lds, const Gemm g, const Sched& S, const Epi& E, const int tid_in) {
;     ...
;                 if (has_next && t == nt - 4) PG8_LOADGA_LDS(ga_nxt);
.LBB0_1014:
	s_andn2_b64 vcc, exec, s[42:43]
	s_cbranch_vccnz .LBB0_1001
	s_waitcnt vmcnt(12)
	s_branch .LBB0_1001
.Lpk_g1_1002:
	s_cmpk_lg_i32 s36, 0x200
	s_cselect_b64 s[42:43], -1, 0
	s_xor_b64 s[60:61], s[44:45], -1
	s_or_b64 s[42:43], s[60:61], s[42:43]
	s_and_b64 vcc, exec, s[42:43]
	s_cbranch_vccnz .Lpk_g1_1004
	ds_read2st64_b32 v[0:1], v246 offset1:2
	s_waitcnt lgkmcnt(0)
	v_lshl_add_u32 v215, v0, 10, v67
	v_lshl_add_u32 v213, v1, 10, v67
	ds_read2st64_b32 v[0:1], v247 offset1:2
	s_waitcnt lgkmcnt(0)
	v_lshl_add_u32 v234, v0, 10, v242
	v_lshl_add_u32 v232, v1, 10, v242

; #define PG8_STAGE(bufoff, gbase, voff) do { _Pragma("unroll") for (int _i = 0; _i < 2; ++_i) \
;         __builtin_amdgcn_global_load_lds((const unsigned*)((const char*)(gbase) + (voff)[_i]), (PG8_LAS unsigned*)(lds + (bufoff) + ldsw + _i * 8192), 16, 0, 0); } while (0)
; #define PG8_LDA(dst, b, h) do { _Pragma("unroll") for (int m = 0; m < 4; ++m) _Pragma("unroll") for (int k = 0; k < 2; ++k) dst[m][k] = *(const PG8_LAS bf16x8*)(lds + PG8_SA(b, h) + aoff + m * 2048 + k * 1024); } while (0)
; #define PG8_LDB(dst, b, h) do { _Pragma("unroll") for (int n = 0; n < 2; ++n) _Pragma("unroll") for (int k = 0; k < 2; ++k) dst[n][k] = *(const PG8_LAS bf16x8*)(lds + PG8_SB(b, h) + boff + n * 2048 + k * 1024); } while (0)
; #define PG8_WAIT_VR(relax) do { if (relax) asm volatile("s_waitcnt vmcnt(%0)" :: "n"(8 + Epi::NST) : "memory"); else asm volatile("s_waitcnt vmcnt(8)" ::: "memory"); } while (0)
; template <class Epi, class Sched, bool ALIGN_EPI = false, bool SP2 = false, bool F8 = false, bool GATHER = false>
; __device__ __forceinline__ void gemm_phase(PG8_LAS unsigned char* lds, const Gemm g, const Sched& S, const Epi& E, const int tid_in) {
;     ...
;                 if (last) { vA0s[0] = ga_nxt[0][0]; vA0s[1] = ga_nxt[0][1]; vA1s[0] = ga_nxt[1][0]; vA1s[1] = ga_nxt[1][1]; }
;                 else { vA0s[0] = ga_cur[0][0]; vA0s[1] = ga_cur[0][1]; vA1s[0] = ga_cur[1][0]; vA1s[1] = ga_cur[1][1]; }
;                 vA1c[0] = ga_cur[1][0]; vA1c[1] = ga_cur[1][1];
;             } else { vA0s[0] = vA1s[0] = voffA[0]; vA0s[1] = vA1s[1] = voffA[1]; }
;             const char* a1 = cA + (size_t)(t + 1) * kstep;
;             const char* a2 = last ? nA : cA + (size_t)(t + 2) * kstep; const char* b2 = last ? nB : cB + (size_t)(t + 2) * kstep;
;             const char* a3 = a2 + kstep; const char* b3 = b2 + kstep;
;             if (last && has_next) S.a_ready(nxt);
;             const bool relax = SP2 && ALIGN_EPI && t == 0 && ui > 0;
;             if constexpr (SP2) {
;             PG8_LDB(B0, 0, 0); PG8_LDB(B1, 0, 1); PG8_SCHED; PG8_LDA(At, 0, 0); if (!relax) PG8_STAGE(PG8_SA(1, 1), a1 + hstepA, vA1c);
;             PG8_WAIT_VR(relax); PG8_WAIT_L(0); PG8_BAR; PG8_MMA(0, 0, At, B0); PG8_MMA(0, 1, At, B1); PG8_BAR; PG8_SCHED;
;             PG8_LDA(At, 0, 1); PG8_STAGE(PG8_SB(0, 0), b2, voffB); PG8_STAGE(PG8_SB(0, 1), b2 + hstep, voffB); PG8_STAGE(PG8_SA(0, 0), a2, vA0s);
.Lpk_g1_1008:
	s_xor_b64 s[64:65], s[42:43], -1
	s_add_u32 s42, s16, s36
	s_addc_u32 s43, s17, s37
	s_add_u32 s62, s42, 0xcf000100
	s_addc_u32 s63, s43, 0
	s_add_u32 s66, s35, s36
	s_addc_u32 s67, s53, s37
	s_cmpk_eq_i32 s36, 0x300
	s_cselect_b64 s[42:43], -1, 0
	s_waitcnt lgkmcnt(0)
	s_and_b64 s[60:61], s[42:43], exec
	v_cndmask_b32_e64 v220, v210, v234, s[42:43]
	v_cndmask_b32_e64 v222, v208, v215, s[42:43]
	s_cselect_b32 s63, s31, s63
	s_cselect_b32 s62, s30, s62
	s_cselect_b32 s61, s3, s67
	s_cselect_b32 s60, s34, s66
	s_barrier
	s_setprio 1
	s_waitcnt lgkmcnt(0)
	v_mfma_f32_16x16x128_f8f6f4 v[192:195], v[26:33], v[58:65], 0
	v_mfma_f32_16x16x128_f8f6f4 v[188:191], v[18:25], v[58:65], 0
	v_mfma_f32_16x16x128_f8f6f4 v[176:179], v[26:33], v[50:57], 0
	v_mfma_f32_16x16x128_f8f6f4 v[172:175], v[18:25], v[50:57], 0
	v_mfma_f32_16x16x128_f8f6f4 v[160:163], v[26:33], v[42:49], 0
	v_mfma_f32_16x16x128_f8f6f4 v[156:159], v[18:25], v[42:49], 0
	v_mfma_f32_16x16x128_f8f6f4 v[144:147], v[26:33], v[34:41], 0
	v_mfma_f32_16x16x128_f8f6f4 v[140:143], v[18:25], v[34:41], 0
	s_setprio 0
	s_setprio 1
	v_mfma_f32_16x16x128_f8f6f4 v[184:187], v[8:15], v[58:65], 0
	v_mfma_f32_16x16x128_f8f6f4 v[180:183], v[0:7], v[58:65], 0
	v_mfma_f32_16x16x128_f8f6f4 v[168:171], v[8:15], v[50:57], 0
	v_mfma_f32_16x16x128_f8f6f4 v[164:167], v[0:7], v[50:57], 0
	v_mfma_f32_16x16x128_f8f6f4 v[152:155], v[8:15], v[42:49], 0
	v_mfma_f32_16x16x128_f8f6f4 v[148:151], v[0:7], v[42:49], 0
	v_mfma_f32_16x16x128_f8f6f4 v[136:139], v[8:15], v[34:41], 0
	v_mfma_f32_16x16x128_f8f6f4 v[132:135], v[0:7], v[34:41], 0
	s_setprio 0
	s_barrier
	s_mov_b32 m0, s77
	v_lshl_add_u64 v[224:225], s[60:61], 0, v[202:203]
	s_add_u32 s66, s60, 0x20000
	ds_read_b128 v[58:61], v231 offset:16384
	ds_read_b128 v[62:65], v231 offset:17408
	ds_read_b128 v[50:53], v231 offset:18432
	ds_read_b128 v[54:57], v231 offset:19456
	ds_read_b128 v[42:45], v231 offset:20480
	ds_read_b128 v[46:49], v231 offset:21504
	ds_read_b128 v[34:37], v231 offset:22528
	ds_read_b128 v[38:41], v231 offset:23552
	global_load_lds_dwordx4 v[224:225], off
	v_lshl_add_u64 v[226:227], s[60:61], 0, v[204:205]
	s_mov_b32 m0, s78
	s_addc_u32 s67, s61, 0
	global_load_lds_dwordx4 v[226:227], off
	v_lshl_add_u64 v[196:197], s[66:67], 0, v[202:203]
	s_mov_b32 m0, s79
	s_and_b64 vcc, exec, s[64:65]
	global_load_lds_dwordx4 v[196:197], off
	v_lshl_add_u64 v[196:197], s[66:67], 0, v[204:205]
	s_mov_b32 m0, s80
	s_mov_b64 s[66:67], -1
	global_load_lds_dwordx4 v[196:197], off
	s_mov_b32 m0, s76
	s_nop 0
	global_load_lds_dwordx4 v222, s[62:63]
	s_mov_b32 m0, s81
	s_nop 0
	global_load_lds_dwordx4 v220, s[62:63]
	s_cbranch_vccz .Lpk_g1_1010
	s_waitcnt vmcnt(8)
	s_mov_b64 s[66:67], 0

; #define PG8_STAGE(bufoff, gbase, voff) do { _Pragma("unroll") for (int _i = 0; _i < 2; ++_i) \
;         __builtin_amdgcn_global_load_lds((const unsigned*)((const char*)(gbase) + (voff)[_i]), (PG8_LAS unsigned*)(lds + (bufoff) + ldsw + _i * 8192), 16, 0, 0); } while (0)
; #define PG8_LDA(dst, b, h) do { _Pragma("unroll") for (int m = 0; m < 4; ++m) _Pragma("unroll") for (int k = 0; k < 2; ++k) dst[m][k] = *(const PG8_LAS bf16x8*)(lds + PG8_SA(b, h) + aoff + m * 2048 + k * 1024); } while (0)
; #define PG8_WAIT_L(n) asm volatile("s_waitcnt lgkmcnt(" #n ")" ::: "memory")
; #define PG8_BAR __builtin_amdgcn_s_barrier()
; template <class Epi, class Sched, bool ALIGN_EPI = false, bool SP2 = false, bool F8 = false, bool GATHER = false>
; __device__ __forceinline__ void gemm_phase(PG8_LAS unsigned char* lds, const Gemm g, const Sched& S, const Epi& E, const int tid_in) {
;     ...
;                 if (last) { vA0s[0] = ga_nxt[0][0]; vA0s[1] = ga_nxt[0][1]; vA1s[0] = ga_nxt[1][0]; vA1s[1] = ga_nxt[1][1]; }
;                 else { vA0s[0] = ga_cur[0][0]; vA0s[1] = ga_cur[0][1]; vA1s[0] = ga_cur[1][0]; vA1s[1] = ga_cur[1][1]; }
;                 vA1c[0] = ga_cur[1][0]; vA1c[1] = ga_cur[1][1];
;             } else { vA0s[0] = vA1s[0] = voffA[0]; vA0s[1] = vA1s[1] = voffA[1]; }
;             const char* a1 = cA + (size_t)(t + 1) * kstep;
;             const char* a2 = last ? nA : cA + (size_t)(t + 2) * kstep; const char* b2 = last ? nB : cB + (size_t)(t + 2) * kstep;
;             const char* a3 = a2 + kstep; const char* b3 = b2 + kstep;
;             if (last && has_next) S.a_ready(nxt);
;             const bool relax = SP2 && ALIGN_EPI && t == 0 && ui > 0;
;             if constexpr (SP2) {
;             PG8_LDB(B0, 0, 0); PG8_LDB(B1, 0, 1); PG8_SCHED; PG8_LDA(At, 0, 0); if (!relax) PG8_STAGE(PG8_SA(1, 1), a1 + hstepA, vA1c);
;             PG8_WAIT_VR(relax); PG8_WAIT_L(0); PG8_BAR; PG8_MMA(0, 0, At, B0); PG8_MMA(0, 1, At, B1); PG8_BAR; PG8_SCHED;
;             PG8_LDA(At, 0, 1); PG8_STAGE(PG8_SB(0, 0), b2, voffB); PG8_STAGE(PG8_SB(0, 1), b2 + hstep, voffB); PG8_STAGE(PG8_SA(0, 0), a2, vA0s);
;             PG8_WAIT_VR(relax); PG8_WAIT_L(0); PG8_BAR; PG8_MMA(1, 0, At, B0); PG8_MMA(1, 1, At, B1); PG8_BAR; PG8_SCHED;
;             PG8_LDB(B0, 1, 0); PG8_LDB(B1, 1, 1); PG8_SCHED; PG8_LDA(At, 1, 0); PG8_STAGE(PG8_SA(0, 1), a2 + hstepA, vA1s);
.Lpk_g1_1012:
	s_waitcnt lgkmcnt(0)
	v_cndmask_b32_e64 v196, v214, v232, s[42:43]
	v_cndmask_b32_e64 v197, v212, v213, s[42:43]
	s_barrier
	s_setprio 1
	s_waitcnt lgkmcnt(0)
	v_mfma_f32_16x16x128_f8f6f4 v[128:131], v[26:33], v[58:65], 0
	v_mfma_f32_16x16x128_f8f6f4 v[124:127], v[18:25], v[58:65], 0
	v_mfma_f32_16x16x128_f8f6f4 v[112:115], v[26:33], v[50:57], 0
	v_mfma_f32_16x16x128_f8f6f4 v[108:111], v[18:25], v[50:57], 0
	v_mfma_f32_16x16x128_f8f6f4 v[96:99], v[26:33], v[42:49], 0
	v_mfma_f32_16x16x128_f8f6f4 v[92:95], v[18:25], v[42:49], 0
	v_mfma_f32_16x16x128_f8f6f4 v[80:83], v[26:33], v[34:41], 0
	v_mfma_f32_16x16x128_f8f6f4 v[76:79], v[18:25], v[34:41], 0
	s_setprio 0
	s_setprio 1
	v_mfma_f32_16x16x128_f8f6f4 v[120:123], v[8:15], v[58:65], 0
	v_mfma_f32_16x16x128_f8f6f4 v[116:119], v[0:7], v[58:65], 0
	v_mfma_f32_16x16x128_f8f6f4 v[104:107], v[8:15], v[50:57], 0
	v_mfma_f32_16x16x128_f8f6f4 v[100:103], v[0:7], v[50:57], 0
	v_mfma_f32_16x16x128_f8f6f4 v[88:91], v[8:15], v[42:49], 0
	v_mfma_f32_16x16x128_f8f6f4 v[84:87], v[0:7], v[42:49], 0
	v_mfma_f32_16x16x128_f8f6f4 v[72:75], v[8:15], v[34:41], 0
	v_mfma_f32_16x16x128_f8f6f4 v[68:71], v[0:7], v[34:41], 0
	s_setprio 0
	s_barrier
	v_add_u32_e32 v0, 0x18000, v249
	v_add_u32_e32 v4, 0x1c000, v249
	ds_read_b128 v[26:29], v0
	ds_read_b128 v[30:33], v0 offset:1024
	ds_read_b128 v[18:21], v0 offset:2048
	ds_read_b128 v[22:25], v0 offset:3072
	ds_read_b128 v[8:11], v4
	ds_read_b128 v[12:15], v4 offset:1024
	ds_read_b128 v[0:3], v4 offset:2048
	ds_read_b128 v[4:7], v4 offset:3072
	s_mov_b32 m0, s82
	ds_read_b128 v[58:61], v231 offset:32768
	ds_read_b128 v[62:65], v231 offset:33792
	ds_read_b128 v[50:53], v231 offset:34816
	ds_read_b128 v[54:57], v231 offset:35840
	ds_read_b128 v[42:45], v231 offset:36864
	ds_read_b128 v[46:49], v231 offset:37888
	ds_read_b128 v[34:37], v231 offset:38912
	ds_read_b128 v[38:41], v231 offset:39936
	global_load_lds_dwordx4 v197, s[62:63]
	s_mov_b32 m0, s83
	s_mov_b64 s[42:43], -1
	global_load_lds_dwordx4 v196, s[62:63]
	s_and_b64 vcc, exec, s[64:65]
	s_mov_b32 s66, s27
	s_mov_b32 s67, s24
	s_cbranch_vccz .Lpk_g1_1014
	s_waitcnt vmcnt(8)
	s_mov_b64 s[42:43], 0

; #define PG8_LAS __attribute__((address_space(3)))
; template <class Epi, class Sched, bool ALIGN_EPI = false, bool SP2 = false, bool F8 = false, bool GATHER = false>
; __device__ __forceinline__ void gemm_phase(PG8_LAS unsigned char* lds, const Gemm g, const Sched& S, const Epi& E, const int tid_in) {
;     ...
;         const bool has_next = S.next(ui + 1, nxt); nxt.par = (ui + 1) & 1;
;         if constexpr (GATHER) { if (has_next && wid == 0)
;             __builtin_amdgcn_global_load_lds((const unsigned*)(g.rowmap + (size_t)nxt.pm * BM + 4 * lane), (PG8_LAS unsigned*)(lds + ROWMAP_LDS_OFF), 16, 0, 0); }
;         const char* nA = (has_next && !GATHER) ? (const char*)g.A + (size_t)nxt.pm * tstep : cA;
;         if constexpr (GATHER) { _Pragma("unroll") for (int _h = 0; _h < 2; ++_h) _Pragma("unroll") for (int _i = 0; _i < 2; ++_i) ga_nxt[_h][_i] = ga_cur[_h][_i]; } const char* nB = has_next ? (const char*)g.Bt + (size_t)nxt.e * g.bstride + (size_t)nxt.pn * tstep : cB;
;     ...
;         for (int a = 0; a < 2; ++a)
; #pragma unroll
;             for (int b = 0; b < 2; ++b)
; #pragma unroll
;                 for (int m = 0; m < 4; ++m)
; #pragma unroll
;                     for (int n = 0; n < 2; ++n) acc[a][b][m][n] = (f32x4){0.f, 0.f, 0.f, 0.f};
;         cur = nxt; cA = nA; cB = nB; ++ui; E.prefetch(cur, wid, lane, lds);
.LBB0_1108:
	s_ashr_i32 s49, s48, 31
	s_lshl_b64 s[52:53], s[48:49], 18
	v_readlane_b32 s54, v252, 29
	v_readlane_b32 s55, v252, 30
	s_add_u32 s52, s54, s52
	s_addc_u32 s53, s55, s53
	s_and_b64 s[54:55], s[40:41], exec
	s_cselect_b32 s3, s53, s43
	s_cselect_b32 s49, s52, s42
	s_ashr_i32 s51, s50, 31
	s_lshl_b64 s[54:55], s[50:51], 20
	s_add_u32 s59, s76, s54
	s_addc_u32 s62, s77, s55
	s_ashr_i32 s37, s36, 31
	s_lshl_b64 s[54:55], s[36:37], 18
	s_add_u32 s54, s59, s54
	s_addc_u32 s55, s62, s55
	s_and_b64 s[62:63], s[40:41], exec
	s_cselect_b32 s37, s55, s61
	s_cselect_b32 s91, s54, s60
	s_cmp_lg_u32 s58, 0
	s_cselect_b64 s[58:59], -1, 0
	s_add_u32 s62, s42, 0x20080
	s_addc_u32 s63, s43, 0
	s_add_u32 s92, s60, 0x100
	v_lshl_add_u64 v[214:215], s[62:63], 0, v[210:211]
	v_lshl_add_u64 v[216:217], s[62:63], 0, v[212:213]
	s_addc_u32 s93, s61, 0
	s_mov_b32 s94, -2
	s_mov_b64 s[60:61], 0
	s_branch .Lpk_g2_1110

; #define PG8_STAGE(bufoff, gbase, voff) do { _Pragma("unroll") for (int _i = 0; _i < 2; ++_i) \
;         __builtin_amdgcn_global_load_lds((const unsigned*)((const char*)(gbase) + (voff)[_i]), (PG8_LAS unsigned*)(lds + (bufoff) + ldsw + _i * 8192), 16, 0, 0); } while (0)
; #define PG8_LDA(dst, b, h) do { _Pragma("unroll") for (int m = 0; m < 4; ++m) _Pragma("unroll") for (int k = 0; k < 2; ++k) dst[m][k] = *(const PG8_LAS bf16x8*)(lds + PG8_SA(b, h) + aoff + m * 2048 + k * 1024); } while (0)
; #define PG8_LDB(dst, b, h) do { _Pragma("unroll") for (int n = 0; n < 2; ++n) _Pragma("unroll") for (int k = 0; k < 2; ++k) dst[n][k] = *(const PG8_LAS bf16x8*)(lds + PG8_SB(b, h) + boff + n * 2048 + k * 1024); } while (0)
; #define PG8_WAIT_VR(relax) do { if (relax) asm volatile("s_waitcnt vmcnt(%0)" :: "n"(8 + Epi::NST) : "memory"); else asm volatile("s_waitcnt vmcnt(8)" ::: "memory"); } while (0)
; #define PG8_WAIT_L(n) asm volatile("s_waitcnt lgkmcnt(" #n ")" ::: "memory")
; #define PG8_BAR __builtin_amdgcn_s_barrier()
; #define PG8_SCHED __builtin_amdgcn_sched_barrier(0)
; template <class Epi, class Sched, bool ALIGN_EPI = false, bool SP2 = false, bool F8 = false, bool GATHER = false>
; __device__ __forceinline__ void gemm_phase(PG8_LAS unsigned char* lds, const Gemm g, const Sched& S, const Epi& E, const int tid_in) {
;     ...
;             PG8_LDB(B0, 0, 0); PG8_LDB(B1, 0, 1); PG8_SCHED; PG8_LDA(At, 0, 0); if (!relax) PG8_STAGE(PG8_SA(1, 1), a1 + hstepA, vA1c);
;             PG8_WAIT_VR(relax); PG8_WAIT_L(0); PG8_BAR; PG8_MMA(0, 0, At, B0); PG8_MMA(0, 1, At, B1); PG8_BAR; PG8_SCHED;
.LBB0_1120:
	s_andn2_b64 vcc, exec, s[66:67]
	s_cbranch_vccnz .LBB0_1109
	s_waitcnt vmcnt(16)
	s_branch .LBB0_1109
.Lpk_g2_1110:
	v_add_u32_e32 v0, 0x10000, v234
	v_add_u32_e32 v4, 0x14000, v234
	ds_read_b128 v[26:29], v0
	ds_read_b128 v[30:33], v0 offset:1024
	ds_read_b128 v[18:21], v0 offset:2048
	ds_read_b128 v[22:25], v0 offset:3072
	ds_read_b128 v[8:11], v4
	ds_read_b128 v[12:15], v4 offset:1024
	ds_read_b128 v[0:3], v4 offset:2048
	ds_read_b128 v[4:7], v4 offset:3072
	s_cmp_eq_u32 s60, 0
	s_cselect_b64 s[62:63], -1, 0
	ds_read_b128 v[58:61], v242
	ds_read_b128 v[62:65], v242 offset:1024
	ds_read_b128 v[50:53], v242 offset:2048
	ds_read_b128 v[54:57], v242 offset:3072
	ds_read_b128 v[42:45], v242 offset:4096
	ds_read_b128 v[46:49], v242 offset:5120
	ds_read_b128 v[34:37], v242 offset:6144
	ds_read_b128 v[38:41], v242 offset:7168
	s_and_b64 s[62:63], s[58:59], s[62:63]
	s_mov_b64 s[64:65], -1
	s_and_b64 vcc, exec, s[62:63]
	s_cbranch_vccnz .Lpk_g2_1112
	v_lshl_add_u64 v[196:197], v[214:215], 0, s[60:61]
	s_add_i32 m0, s25, 0xc000
	s_mov_b64 s[64:65], 0
	global_load_lds_dwordx4 v[196:197], off
	v_lshl_add_u64 v[196:197], v[216:217], 0, s[60:61]
	s_add_i32 m0, s25, 0xe000
	s_nop 0
	global_load_lds_dwordx4 v[196:197], off
	s_waitcnt vmcnt(8)

; #define PG8_STAGE(bufoff, gbase, voff) do { _Pragma("unroll") for (int _i = 0; _i < 2; ++_i) \
;         __builtin_amdgcn_global_load_lds((const unsigned*)((const char*)(gbase) + (voff)[_i]), (PG8_LAS unsigned*)(lds + (bufoff) + ldsw + _i * 8192), 16, 0, 0); } while (0)
; #define PG8_LDA(dst, b, h) do { _Pragma("unroll") for (int m = 0; m < 4; ++m) _Pragma("unroll") for (int k = 0; k < 2; ++k) dst[m][k] = *(const PG8_LAS bf16x8*)(lds + PG8_SA(b, h) + aoff + m * 2048 + k * 1024); } while (0)
; #define PG8_LDB(dst, b, h) do { _Pragma("unroll") for (int n = 0; n < 2; ++n) _Pragma("unroll") for (int k = 0; k < 2; ++k) dst[n][k] = *(const PG8_LAS bf16x8*)(lds + PG8_SB(b, h) + boff + n * 2048 + k * 1024); } while (0)
; #define PG8_WAIT_VR(relax) do { if (relax) asm volatile("s_waitcnt vmcnt(%0)" :: "n"(8 + Epi::NST) : "memory"); else asm volatile("s_waitcnt vmcnt(8)" ::: "memory"); } while (0)
; #define PG8_WAIT_L(n) asm volatile("s_waitcnt lgkmcnt(" #n ")" ::: "memory")
; #define PG8_BAR __builtin_amdgcn_s_barrier()
; #define PG8_SCHED __builtin_amdgcn_sched_barrier(0)
; template <class Epi, class Sched, bool ALIGN_EPI = false, bool SP2 = false, bool F8 = false, bool GATHER = false>
; __device__ __forceinline__ void gemm_phase(PG8_LAS unsigned char* lds, const Gemm g, const Sched& S, const Epi& E, const int tid_in) {
;     ...
;             const char* a2 = last ? nA : cA + (size_t)(t + 2) * kstep; const char* b2 = last ? nB : cB + (size_t)(t + 2) * kstep;
;             const char* a3 = a2 + kstep; const char* b3 = b2 + kstep;
;             if (last && has_next) S.a_ready(nxt);
;             const bool relax = SP2 && ALIGN_EPI && t == 0 && ui > 0;
;             if constexpr (SP2) {
;             PG8_LDB(B0, 0, 0); PG8_LDB(B1, 0, 1); PG8_SCHED; PG8_LDA(At, 0, 0); if (!relax) PG8_STAGE(PG8_SA(1, 1), a1 + hstepA, vA1c);
;             PG8_WAIT_VR(relax); PG8_WAIT_L(0); PG8_BAR; PG8_MMA(0, 0, At, B0); PG8_MMA(0, 1, At, B1); PG8_BAR; PG8_SCHED;
;             PG8_LDA(At, 0, 1); PG8_STAGE(PG8_SB(0, 0), b2, voffB); PG8_STAGE(PG8_SB(0, 1), b2 + hstep, voffB); PG8_STAGE(PG8_SA(0, 0), a2, vA0s);
.Lpk_g2_1114:
	s_xor_b64 s[64:65], s[62:63], -1
	s_add_u32 s62, s42, s60
	s_addc_u32 s63, s43, s61
	s_add_u32 s62, s62, 0x100
	s_addc_u32 s63, s63, 0
	s_add_u32 s72, s92, s60
	s_addc_u32 s73, s93, s61
	s_waitcnt lgkmcnt(0)
	s_cmpk_eq_i32 s60, 0x300
	s_cselect_b32 s67, s3, s63
	s_cselect_b32 s66, s49, s62
	s_cselect_b32 s63, s37, s73
	s_cselect_b32 s62, s91, s72
	s_barrier
	s_setprio 1
	s_waitcnt lgkmcnt(0)
	v_mfma_f32_16x16x128_f8f6f4 v[192:195], v[26:33], v[58:65], 0
	v_mfma_f32_16x16x128_f8f6f4 v[188:191], v[18:25], v[58:65], 0
	v_mfma_f32_16x16x128_f8f6f4 v[184:187], v[26:33], v[50:57], 0
	v_mfma_f32_16x16x128_f8f6f4 v[180:183], v[18:25], v[50:57], 0
	v_mfma_f32_16x16x128_f8f6f4 v[160:163], v[26:33], v[42:49], 0
	v_mfma_f32_16x16x128_f8f6f4 v[156:159], v[18:25], v[42:49], 0
	v_mfma_f32_16x16x128_f8f6f4 v[152:155], v[26:33], v[34:41], 0
	v_mfma_f32_16x16x128_f8f6f4 v[148:151], v[18:25], v[34:41], 0
	s_setprio 0
	s_setprio 1
	v_mfma_f32_16x16x128_f8f6f4 v[176:179], v[8:15], v[58:65], 0
	v_mfma_f32_16x16x128_f8f6f4 v[172:175], v[0:7], v[58:65], 0
	v_mfma_f32_16x16x128_f8f6f4 v[168:171], v[8:15], v[50:57], 0
	v_mfma_f32_16x16x128_f8f6f4 v[164:167], v[0:7], v[50:57], 0
	v_mfma_f32_16x16x128_f8f6f4 v[144:147], v[8:15], v[42:49], 0
	v_mfma_f32_16x16x128_f8f6f4 v[140:143], v[0:7], v[42:49], 0
	v_mfma_f32_16x16x128_f8f6f4 v[136:139], v[8:15], v[34:41], 0
	v_mfma_f32_16x16x128_f8f6f4 v[132:135], v[0:7], v[34:41], 0
	s_setprio 0
	s_barrier
	s_mov_b32 m0, s57
	v_lshl_add_u64 v[218:219], s[62:63], 0, v[204:205]
	s_add_u32 s72, s62, 0x20000
	ds_read_b128 v[58:61], v242 offset:16384
	ds_read_b128 v[62:65], v242 offset:17408
	ds_read_b128 v[50:53], v242 offset:18432
	ds_read_b128 v[54:57], v242 offset:19456
	ds_read_b128 v[42:45], v242 offset:20480
	ds_read_b128 v[46:49], v242 offset:21504
	ds_read_b128 v[34:37], v242 offset:22528
	ds_read_b128 v[38:41], v242 offset:23552
	global_load_lds_dwordx4 v[218:219], off
	v_lshl_add_u64 v[220:221], s[62:63], 0, v[208:209]
	s_mov_b32 m0, s69
	s_addc_u32 s73, s63, 0
	global_load_lds_dwordx4 v[220:221], off
	v_lshl_add_u64 v[196:197], s[72:73], 0, v[204:205]
	s_mov_b32 m0, s78
	v_lshl_add_u64 v[222:223], s[66:67], 0, v[202:203]
	global_load_lds_dwordx4 v[196:197], off
	v_lshl_add_u64 v[196:197], s[72:73], 0, v[208:209]
	s_mov_b32 m0, s79
	v_lshl_add_u64 v[224:225], s[66:67], 0, v[206:207]
	global_load_lds_dwordx4 v[196:197], off
	s_mov_b32 m0, s25
	s_mov_b64 s[72:73], -1
	global_load_lds_dwordx4 v[222:223], off
	s_mov_b32 m0, s80
	s_and_b64 vcc, exec, s[64:65]
	global_load_lds_dwordx4 v[224:225], off
	s_cbranch_vccz .Lpk_g2_1116
	s_waitcnt vmcnt(8)
	s_mov_b64 s[72:73], 0

; #define PG8_STAGE(bufoff, gbase, voff) do { _Pragma("unroll") for (int _i = 0; _i < 2; ++_i) \
;         __builtin_amdgcn_global_load_lds((const unsigned*)((const char*)(gbase) + (voff)[_i]), (PG8_LAS unsigned*)(lds + (bufoff) + ldsw + _i * 8192), 16, 0, 0); } while (0)
; #define PG8_LDA(dst, b, h) do { _Pragma("unroll") for (int m = 0; m < 4; ++m) _Pragma("unroll") for (int k = 0; k < 2; ++k) dst[m][k] = *(const PG8_LAS bf16x8*)(lds + PG8_SA(b, h) + aoff + m * 2048 + k * 1024); } while (0)
; #define PG8_LDB(dst, b, h) do { _Pragma("unroll") for (int n = 0; n < 2; ++n) _Pragma("unroll") for (int k = 0; k < 2; ++k) dst[n][k] = *(const PG8_LAS bf16x8*)(lds + PG8_SB(b, h) + boff + n * 2048 + k * 1024); } while (0)
; #define PG8_WAIT_VR(relax) do { if (relax) asm volatile("s_waitcnt vmcnt(%0)" :: "n"(8 + Epi::NST) : "memory"); else asm volatile("s_waitcnt vmcnt(8)" ::: "memory"); } while (0)
; #define PG8_WAIT_L(n) asm volatile("s_waitcnt lgkmcnt(" #n ")" ::: "memory")
; #define PG8_BAR __builtin_amdgcn_s_barrier()
; #define PG8_SCHED __builtin_amdgcn_sched_barrier(0)
; template <class Epi, class Sched, bool ALIGN_EPI = false, bool SP2 = false, bool F8 = false, bool GATHER = false>
; __device__ __forceinline__ void gemm_phase(PG8_LAS unsigned char* lds, const Gemm g, const Sched& S, const Epi& E, const int tid_in) {
;     ...
;             PG8_WAIT_VR(relax); PG8_WAIT_L(0); PG8_BAR; PG8_MMA(1, 0, At, B0); PG8_MMA(1, 1, At, B1); PG8_BAR; PG8_SCHED;
;             PG8_LDB(B0, 1, 0); PG8_LDB(B1, 1, 1); PG8_SCHED; PG8_LDA(At, 1, 0); PG8_STAGE(PG8_SA(0, 1), a2 + hstepA, vA1s);
;             PG8_WAIT_VR(relax); PG8_WAIT_L(0); PG8_BAR; PG8_MMA(0, 0, At, B0); PG8_MMA(0, 1, At, B1); PG8_BAR; PG8_SCHED;
.Lpk_g2_1118:
	s_waitcnt lgkmcnt(0)
	s_barrier
	s_setprio 1
	s_waitcnt lgkmcnt(0)
	v_mfma_f32_16x16x128_f8f6f4 v[128:131], v[26:33], v[58:65], 0
	v_mfma_f32_16x16x128_f8f6f4 v[124:127], v[18:25], v[58:65], 0
	v_mfma_f32_16x16x128_f8f6f4 v[112:115], v[26:33], v[50:57], 0
	v_mfma_f32_16x16x128_f8f6f4 v[108:111], v[18:25], v[50:57], 0
	v_mfma_f32_16x16x128_f8f6f4 v[92:95], v[26:33], v[42:49], 0
	v_mfma_f32_16x16x128_f8f6f4 v[84:87], v[18:25], v[42:49], 0
	v_mfma_f32_16x16x128_f8f6f4 v[72:75], v[26:33], v[34:41], 0
	v_mfma_f32_16x16x128_f8f6f4 v[68:71], v[18:25], v[34:41], 0
	s_setprio 0
	s_setprio 1
	v_mfma_f32_16x16x128_f8f6f4 v[120:123], v[8:15], v[58:65], 0
	v_mfma_f32_16x16x128_f8f6f4 v[116:119], v[0:7], v[58:65], 0
	v_mfma_f32_16x16x128_f8f6f4 v[104:107], v[8:15], v[50:57], 0
	v_mfma_f32_16x16x128_f8f6f4 v[100:103], v[0:7], v[50:57], 0
	v_mfma_f32_16x16x128_f8f6f4 v[96:99], v[8:15], v[42:49], 0
	v_mfma_f32_16x16x128_f8f6f4 v[88:91], v[0:7], v[42:49], 0
	v_mfma_f32_16x16x128_f8f6f4 v[80:83], v[8:15], v[34:41], 0
	v_mfma_f32_16x16x128_f8f6f4 v[76:79], v[0:7], v[34:41], 0
	s_setprio 0
	s_barrier
	v_add_u32_e32 v0, 0x18000, v234
	v_add_u32_e32 v4, 0x1c000, v234
	ds_read_b128 v[26:29], v0
	ds_read_b128 v[30:33], v0 offset:1024
	ds_read_b128 v[18:21], v0 offset:2048
	ds_read_b128 v[22:25], v0 offset:3072
	ds_read_b128 v[8:11], v4
	ds_read_b128 v[12:15], v4 offset:1024
	ds_read_b128 v[0:3], v4 offset:2048
	ds_read_b128 v[4:7], v4 offset:3072
	s_add_u32 s66, s66, 0x20000
	s_addc_u32 s67, s67, 0
	s_mov_b32 m0, s81
	v_lshl_add_u64 v[196:197], s[66:67], 0, v[202:203]
	ds_read_b128 v[58:61], v242 offset:32768
	ds_read_b128 v[62:65], v242 offset:33792
	ds_read_b128 v[50:53], v242 offset:34816
	ds_read_b128 v[54:57], v242 offset:35840
	ds_read_b128 v[42:45], v242 offset:36864
	ds_read_b128 v[46:49], v242 offset:37888
	ds_read_b128 v[34:37], v242 offset:38912
	ds_read_b128 v[38:41], v242 offset:39936
	global_load_lds_dwordx4 v[196:197], off
	v_lshl_add_u64 v[196:197], s[66:67], 0, v[206:207]
	s_mov_b32 m0, s82
	s_mov_b64 s[66:67], -1
	global_load_lds_dwordx4 v[196:197], off
	s_and_b64 vcc, exec, s[64:65]
	s_cbranch_vccz .Lpk_g2_1120
	s_waitcnt vmcnt(8)
	s_mov_b64 s[66:67], 0
